# v107 + sparse phase start: the three binary searches over the LDS prefixes replaced by two-level parallel (ballot) searches
# speedup vs baseline: 1.0081x; 1.0031x over previous
.LBB0_798:
	v_mbcnt_lo_u32_b32 v60, -1, 0
	v_mbcnt_hi_u32_b32 v60, -1, v60
	v_lshlrev_b32_e32 v61, 6, v60
	v_add_u32_e32 v61, 0x2283c, v61
	ds_read_b32 v61, v61
	s_waitcnt lgkmcnt(0)
	v_cmp_ge_u32_e64 s[100:101], s6, v61
	s_bcnt1_i32_b64 s99, s[100:101]
	s_min_u32 s99, s99, 63
	s_lshl_b32 s100, s99, 6
	v_lshl_add_u32 v61, v60, 2, s100
	v_add_u32_e32 v61, 0x22800, v61
	ds_read_b32 v61, v61
	s_waitcnt lgkmcnt(0)
	v_cmp_ge_u32_e64 s[100:101], s6, v61
	s_and_b32 s100, s100, 0xffff
	s_bcnt1_i32_b32 s100, s100
	s_lshl_b32 s4, s99, 4
	s_add_i32 s4, s4, s100
	s_add_i32 s4, s4, -1
	s_lshl_b32 s4, s4, 2
	s_add_i32 s4, s4, 0
	s_add_i32 s5, s4, 0x21400
	s_add_i32 s4, s4, 0x22800
	v_mov_b32_e32 v4, s5
	v_mov_b32_e32 v8, s4
	ds_read2_b32 v[4:5], v4 offset1:1
	ds_read_b32 v8, v8
	s_waitcnt lgkmcnt(1)
	v_readfirstlane_b32 s4, v4
	s_waitcnt lgkmcnt(0)
	v_readfirstlane_b32 s10, v8
	v_readfirstlane_b32 s5, v5
	s_add_i32 s11, s10, 6
	s_sub_i32 s10, s6, s10
	s_sub_i32 s7, s5, s4
	s_add_i32 s10, s10, 1
	s_lshr_b32 s10, s10, 3
	s_cmp_lt_u32 s11, s6
	s_cselect_b32 s6, s10, 0
	s_add_i32 s4, s6, s4
	s_cmp_lt_u32 s6, s7
	s_cselect_b32 s66, s4, s5

.LBB0_805:
	v_mbcnt_lo_u32_b32 v60, -1, 0
	v_mbcnt_hi_u32_b32 v60, -1, v60
	v_lshlrev_b32_e32 v61, 6, v60
	v_add_u32_e32 v61, 0x2283c, v61
	ds_read_b32 v61, v61
	s_waitcnt lgkmcnt(0)
	v_cmp_ge_u32_e64 s[100:101], s6, v61
	s_bcnt1_i32_b64 s99, s[100:101]
	s_min_u32 s99, s99, 63
	s_lshl_b32 s100, s99, 6
	v_lshl_add_u32 v61, v60, 2, s100
	v_add_u32_e32 v61, 0x22800, v61
	ds_read_b32 v61, v61
	s_waitcnt lgkmcnt(0)
	v_cmp_ge_u32_e64 s[100:101], s6, v61
	s_and_b32 s100, s100, 0xffff
	s_bcnt1_i32_b32 s100, s100
	s_lshl_b32 s4, s99, 4
	s_add_i32 s4, s4, s100
	s_add_i32 s4, s4, -1
	s_lshl_b32 s4, s4, 2
	s_add_i32 s4, s4, 0
	s_add_i32 s5, s4, 0x21400
	s_add_i32 s4, s4, 0x22800
	v_mov_b32_e32 v2, s5
	v_mov_b32_e32 v4, s4
	ds_read2_b32 v[2:3], v2 offset1:1
	ds_read_b32 v4, v4
	s_waitcnt lgkmcnt(1)
	v_sub_u32_e32 v5, v3, v2
	s_waitcnt lgkmcnt(0)
	v_add_u32_e32 v8, 6, v4
	v_sub_u32_e32 v4, s6, v4
	v_add_u32_e32 v4, 1, v4
	v_lshrrev_b32_e32 v4, 3, v4
	v_cmp_gt_u32_e32 vcc, s6, v8
	s_nop 1
	v_cndmask_b32_e32 v4, 0, v4, vcc
	v_add_u32_e32 v2, v4, v2
	v_cmp_lt_u32_e32 vcc, v4, v5
	s_nop 1
	v_cndmask_b32_e32 v186, v3, v2, vcc

.LBB0_809:
	v_mbcnt_lo_u32_b32 v60, -1, 0
	v_mbcnt_hi_u32_b32 v60, -1, v60
	v_lshlrev_b32_e32 v61, 6, v60
	v_add_u32_e32 v61, 0x2143c, v61
	ds_read_b32 v61, v61
	s_waitcnt lgkmcnt(0)
	v_cmp_ge_u32_e64 s[100:101], s66, v61
	s_bcnt1_i32_b64 s99, s[100:101]
	s_min_u32 s99, s99, 63
	s_lshl_b32 s100, s99, 6
	v_lshl_add_u32 v61, v60, 2, s100
	v_add_u32_e32 v61, 0x21400, v61
	ds_read_b32 v61, v61
	s_waitcnt lgkmcnt(0)
	v_cmp_ge_u32_e64 s[100:101], s66, v61
	s_and_b32 s100, s100, 0xffff
	s_bcnt1_i32_b32 s100, s100
	s_lshl_b32 s4, s99, 4
	s_add_i32 s4, s4, s100
	s_add_i32 s4, s4, -1
	s_lshl_b32 s5, s4, 2
	s_add_i32 s5, s5, 0
	s_add_i32 s7, s5, 0x21400
	s_add_i32 s6, s4, -2
